# loop-head rotation (7.11): prefetch decision and stage math hoisted above the k-loop barrier, post-barrier branch ladder removed in all 7 GEMM k-loops
# baseline (speedup 1.0000x reference)
;     ...
;     auto issue = [&](int kt, int st) {
;         glds_tile8(va, vb, a0p + (size_t)kt * kstepA, Btile + (size_t)kt * 64, __builtin_amdgcn_readfirstlane(lds0 + st * 32768));
;     };
;     ...
;     for (int kt = 0; kt < nk; ++kt) {
;         asm volatile("s_waitcnt vmcnt(0)\n\ts_barrier" ::: "memory");
;         if (kt + 1 < nk) issue(kt + 1, (kt + 1) & 1);
.LBB0_72:
	s_add_i32 s69, s68, 0x8000
	s_and_b32 s38, s69, 0x8000
	s_add_i32 s38, s38, s67
	s_cmp_lg_u32 s68, 0x38000
	s_waitcnt vmcnt(0)
	s_barrier
	s_cbranch_scc0 .LBB0_71
	s_mov_b32 s39, m0
	s_mov_b32 m0, s38
	s_nop 0
	global_load_lds_dwordx4 v67, s[0:1]
	s_add_u32 m0, m0, 0x1000
	s_nop 0
	global_load_lds_dwordx4 v69, s[0:1]
	s_add_u32 m0, m0, 0x1000
	s_nop 0
	global_load_lds_dwordx4 v71, s[0:1]
	s_add_u32 m0, m0, 0x1000
	s_nop 0
	global_load_lds_dwordx4 v73, s[0:1]
	s_add_u32 m0, m0, 0x1000
	s_nop 0
	global_load_lds_dwordx4 v68, s[30:31]
	s_add_u32 m0, m0, 0x1000
	s_nop 0
	global_load_lds_dwordx4 v70, s[30:31]
	s_add_u32 m0, m0, 0x1000
	s_nop 0
	global_load_lds_dwordx4 v72, s[30:31]
	s_add_u32 m0, m0, 0x1000
	s_nop 0
	global_load_lds_dwordx4 v74, s[30:31]
	s_mov_b32 m0, s39
	s_branch .LBB0_71

; DEVI void glds_tile8(const unsigned (&va)[4], const unsigned (&vb)[4], const void* sa, const void* sb, unsigned lds) {
;     ...
;     asm volatile(
;         "s_mov_b32 %[keep], m0\n\t"
;         "s_mov_b32 m0, %[l]\n\ts_nop 0\n\tglobal_load_lds_dwordx4 %[a0], %[sa]\n\t"
;         "s_add_u32 m0, m0, 0x1000\n\ts_nop 0\n\tglobal_load_lds_dwordx4 %[a1], %[sa]\n\t"
;         "s_add_u32 m0, m0, 0x1000\n\ts_nop 0\n\tglobal_load_lds_dwordx4 %[a2], %[sa]\n\t"
;         "s_add_u32 m0, m0, 0x1000\n\ts_nop 0\n\tglobal_load_lds_dwordx4 %[a3], %[sa]\n\t"
;         "s_add_u32 m0, m0, 0x1000\n\ts_nop 0\n\tglobal_load_lds_dwordx4 %[b0], %[sb]\n\t"
;         "s_add_u32 m0, m0, 0x1000\n\ts_nop 0\n\tglobal_load_lds_dwordx4 %[b1], %[sb]\n\t"
;         "s_add_u32 m0, m0, 0x1000\n\ts_nop 0\n\tglobal_load_lds_dwordx4 %[b2], %[sb]\n\t"
;         "s_add_u32 m0, m0, 0x1000\n\ts_nop 0\n\tglobal_load_lds_dwordx4 %[b3], %[sb]\n\t"
;         "s_mov_b32 m0, %[keep]"
;         : [keep] "=&s"(keep)
;         : [a0] "v"(va[0]), [a1] "v"(va[1]), [a2] "v"(va[2]), [a3] "v"(va[3]), [b0] "v"(vb[0]), [b1] "v"(vb[1]), [b2] "v"(vb[2]), [b3] "v"(vb[3]),
;           [sa] "s"(sa), [sb] "s"(sb), [l] "s"(lds)
;         : "memory", "scc");
;     ...
;     auto issue = [&](int kt, int st) {
;         glds_tile8(va, vb, a0p + (size_t)kt * kstepA, Btile + (size_t)kt * 64, __builtin_amdgcn_readfirstlane(lds0 + st * 32768));
;     };
;     const int sw0 = (quad ^ (l16 >> 1)) * 16;
;     const int aoffb = (wr * 64 + l16) * 128, boffb = 16384 + (wc * 64 + l16) * 128;
;     if (!first_issued) issue(0, 0);
; #pragma unroll 1
;     for (int kt = 0; kt < nk; ++kt) {
;         asm volatile("s_waitcnt vmcnt(0)\n\ts_barrier" ::: "memory");
;         if (kt + 1 < nk) issue(kt + 1, (kt + 1) & 1);
.LBB0_94:
	s_add_i32 s66, s31, 0x8000
	s_and_b32 s64, s66, 0x8000
	s_add_i32 s64, s64, s22
	s_cmp_lg_u32 s31, 0x78000
	s_waitcnt vmcnt(0)
	s_barrier
	s_cbranch_scc0 .LBB0_93
	s_mov_b32 s65, m0
	s_mov_b32 m0, s64
	s_nop 0
	global_load_lds_dwordx4 v75, s[42:43]
	s_add_u32 m0, m0, 0x1000
	s_nop 0
	global_load_lds_dwordx4 v77, s[42:43]
	s_add_u32 m0, m0, 0x1000
	s_nop 0
	global_load_lds_dwordx4 v79, s[42:43]
	s_add_u32 m0, m0, 0x1000
	s_nop 0
	global_load_lds_dwordx4 v80, s[42:43]
	s_add_u32 m0, m0, 0x1000
	s_nop 0
	global_load_lds_dwordx4 v75, s[40:41]
	s_add_u32 m0, m0, 0x1000
	s_nop 0
	global_load_lds_dwordx4 v77, s[40:41]
	s_add_u32 m0, m0, 0x1000
	s_nop 0
	global_load_lds_dwordx4 v79, s[40:41]
	s_add_u32 m0, m0, 0x1000
	s_nop 0
	global_load_lds_dwordx4 v80, s[40:41]
	s_mov_b32 m0, s65
	s_branch .LBB0_93

; DEVI void glds_tile8(const unsigned (&va)[4], const unsigned (&vb)[4], const void* sa, const void* sb, unsigned lds) {
;     ...
;     asm volatile(
;         "s_mov_b32 %[keep], m0\n\t"
;         "s_mov_b32 m0, %[l]\n\ts_nop 0\n\tglobal_load_lds_dwordx4 %[a0], %[sa]\n\t"
;         "s_add_u32 m0, m0, 0x1000\n\ts_nop 0\n\tglobal_load_lds_dwordx4 %[a1], %[sa]\n\t"
;         "s_add_u32 m0, m0, 0x1000\n\ts_nop 0\n\tglobal_load_lds_dwordx4 %[a2], %[sa]\n\t"
;         "s_add_u32 m0, m0, 0x1000\n\ts_nop 0\n\tglobal_load_lds_dwordx4 %[a3], %[sa]\n\t"
;         "s_add_u32 m0, m0, 0x1000\n\ts_nop 0\n\tglobal_load_lds_dwordx4 %[b0], %[sb]\n\t"
;         "s_add_u32 m0, m0, 0x1000\n\ts_nop 0\n\tglobal_load_lds_dwordx4 %[b1], %[sb]\n\t"
;         "s_add_u32 m0, m0, 0x1000\n\ts_nop 0\n\tglobal_load_lds_dwordx4 %[b2], %[sb]\n\t"
;         "s_add_u32 m0, m0, 0x1000\n\ts_nop 0\n\tglobal_load_lds_dwordx4 %[b3], %[sb]\n\t"
;         "s_mov_b32 m0, %[keep]"
;         : [keep] "=&s"(keep)
;         : [a0] "v"(va[0]), [a1] "v"(va[1]), [a2] "v"(va[2]), [a3] "v"(va[3]), [b0] "v"(vb[0]), [b1] "v"(vb[1]), [b2] "v"(vb[2]), [b3] "v"(vb[3]),
;           [sa] "s"(sa), [sb] "s"(sb), [l] "s"(lds)
;         : "memory", "scc");
;     ...
;     auto issue = [&](int kt, int st) {
;         glds_tile8(va, vb, a0p + (size_t)kt * kstepA, Btile + (size_t)kt * 64, __builtin_amdgcn_readfirstlane(lds0 + st * 32768));
;     };
;     const int sw0 = (quad ^ (l16 >> 1)) * 16;
;     const int aoffb = (wr * 64 + l16) * 128, boffb = 16384 + (wc * 64 + l16) * 128;
;     if (!first_issued) issue(0, 0);
; #pragma unroll 1
;     for (int kt = 0; kt < nk; ++kt) {
;         asm volatile("s_waitcnt vmcnt(0)\n\ts_barrier" ::: "memory");
;         if (kt + 1 < nk) issue(kt + 1, (kt + 1) & 1);
.LBB0_187:
	s_add_i32 s64, s31, 0x8000
	s_and_b32 s46, s64, 0x8000
	s_add_i32 s46, s46, s22
	s_cmp_lg_u32 s31, 0x78000
	s_waitcnt vmcnt(0)
	s_barrier
	s_cbranch_scc0 .LBB0_186
	s_mov_b32 s47, m0
	s_mov_b32 m0, s46
	s_nop 0
	global_load_lds_dwordx4 v75, s[42:43]
	s_add_u32 m0, m0, 0x1000
	s_nop 0
	global_load_lds_dwordx4 v77, s[42:43]
	s_add_u32 m0, m0, 0x1000
	s_nop 0
	global_load_lds_dwordx4 v79, s[42:43]
	s_add_u32 m0, m0, 0x1000
	s_nop 0
	global_load_lds_dwordx4 v80, s[42:43]
	s_add_u32 m0, m0, 0x1000
	s_nop 0
	global_load_lds_dwordx4 v75, s[40:41]
	s_add_u32 m0, m0, 0x1000
	s_nop 0
	global_load_lds_dwordx4 v77, s[40:41]
	s_add_u32 m0, m0, 0x1000
	s_nop 0
	global_load_lds_dwordx4 v79, s[40:41]
	s_add_u32 m0, m0, 0x1000
	s_nop 0
	global_load_lds_dwordx4 v80, s[40:41]
	s_mov_b32 m0, s47
	s_branch .LBB0_186

; DEVI void glds_tile8(const unsigned (&va)[4], const unsigned (&vb)[4], const void* sa, const void* sb, unsigned lds) {
;     ...
;     asm volatile(
;         "s_mov_b32 %[keep], m0\n\t"
;         "s_mov_b32 m0, %[l]\n\ts_nop 0\n\tglobal_load_lds_dwordx4 %[a0], %[sa]\n\t"
;         "s_add_u32 m0, m0, 0x1000\n\ts_nop 0\n\tglobal_load_lds_dwordx4 %[a1], %[sa]\n\t"
;         "s_add_u32 m0, m0, 0x1000\n\ts_nop 0\n\tglobal_load_lds_dwordx4 %[a2], %[sa]\n\t"
;         "s_add_u32 m0, m0, 0x1000\n\ts_nop 0\n\tglobal_load_lds_dwordx4 %[a3], %[sa]\n\t"
;         "s_add_u32 m0, m0, 0x1000\n\ts_nop 0\n\tglobal_load_lds_dwordx4 %[b0], %[sb]\n\t"
;         "s_add_u32 m0, m0, 0x1000\n\ts_nop 0\n\tglobal_load_lds_dwordx4 %[b1], %[sb]\n\t"
;         "s_add_u32 m0, m0, 0x1000\n\ts_nop 0\n\tglobal_load_lds_dwordx4 %[b2], %[sb]\n\t"
;         "s_add_u32 m0, m0, 0x1000\n\ts_nop 0\n\tglobal_load_lds_dwordx4 %[b3], %[sb]\n\t"
;         "s_mov_b32 m0, %[keep]"
;         : [keep] "=&s"(keep)
;         : [a0] "v"(va[0]), [a1] "v"(va[1]), [a2] "v"(va[2]), [a3] "v"(va[3]), [b0] "v"(vb[0]), [b1] "v"(vb[1]), [b2] "v"(vb[2]), [b3] "v"(vb[3]),
;           [sa] "s"(sa), [sb] "s"(sb), [l] "s"(lds)
;         : "memory", "scc");
;     ...
;     auto issue = [&](int kt, int st) {
;         glds_tile8(va, vb, a0p + (size_t)kt * kstepA, Btile + (size_t)kt * 64, __builtin_amdgcn_readfirstlane(lds0 + st * 32768));
;     };
;     const int sw0 = (quad ^ (l16 >> 1)) * 16;
;     const int aoffb = (wr * 64 + l16) * 128, boffb = 16384 + (wc * 64 + l16) * 128;
;     if (!first_issued) issue(0, 0);
; #pragma unroll 1
;     for (int kt = 0; kt < nk; ++kt) {
;         asm volatile("s_waitcnt vmcnt(0)\n\ts_barrier" ::: "memory");
;         if (kt + 1 < nk) issue(kt + 1, (kt + 1) & 1);
.LBB0_210:
	s_add_i32 s64, s47, 0x8000
	s_and_b32 s40, s64, 0x8000
	s_add_i32 s40, s28, s40
	s_cmp_lt_u32 s43, 15
	s_waitcnt vmcnt(0)
	s_barrier
	s_cbranch_scc0 .LBB0_209
	s_mov_b32 s41, m0
	s_mov_b32 m0, s40
	s_nop 0
	global_load_lds_dwordx4 v0, s[38:39]
	s_add_u32 m0, m0, 0x1000
	s_nop 0
	global_load_lds_dwordx4 v68, s[38:39]
	s_add_u32 m0, m0, 0x1000
	s_nop 0
	global_load_lds_dwordx4 v69, s[38:39]
	s_add_u32 m0, m0, 0x1000
	s_nop 0
	global_load_lds_dwordx4 v70, s[38:39]
	s_add_u32 m0, m0, 0x1000
	s_nop 0
	global_load_lds_dwordx4 v0, s[30:31]
	s_add_u32 m0, m0, 0x1000
	s_nop 0
	global_load_lds_dwordx4 v68, s[30:31]
	s_add_u32 m0, m0, 0x1000
	s_nop 0
	global_load_lds_dwordx4 v69, s[30:31]
	s_add_u32 m0, m0, 0x1000
	s_nop 0
	global_load_lds_dwordx4 v70, s[30:31]
	s_mov_b32 m0, s41
	s_branch .LBB0_209

; DEVI void glds_tile8(const unsigned (&va)[4], const unsigned (&vb)[4], const void* sa, const void* sb, unsigned lds) {
;     ...
;     asm volatile(
;         "s_mov_b32 %[keep], m0\n\t"
;         "s_mov_b32 m0, %[l]\n\ts_nop 0\n\tglobal_load_lds_dwordx4 %[a0], %[sa]\n\t"
;         "s_add_u32 m0, m0, 0x1000\n\ts_nop 0\n\tglobal_load_lds_dwordx4 %[a1], %[sa]\n\t"
;         "s_add_u32 m0, m0, 0x1000\n\ts_nop 0\n\tglobal_load_lds_dwordx4 %[a2], %[sa]\n\t"
;         "s_add_u32 m0, m0, 0x1000\n\ts_nop 0\n\tglobal_load_lds_dwordx4 %[a3], %[sa]\n\t"
;         "s_add_u32 m0, m0, 0x1000\n\ts_nop 0\n\tglobal_load_lds_dwordx4 %[b0], %[sb]\n\t"
;         "s_add_u32 m0, m0, 0x1000\n\ts_nop 0\n\tglobal_load_lds_dwordx4 %[b1], %[sb]\n\t"
;         "s_add_u32 m0, m0, 0x1000\n\ts_nop 0\n\tglobal_load_lds_dwordx4 %[b2], %[sb]\n\t"
;         "s_add_u32 m0, m0, 0x1000\n\ts_nop 0\n\tglobal_load_lds_dwordx4 %[b3], %[sb]\n\t"
;         "s_mov_b32 m0, %[keep]"
;         : [keep] "=&s"(keep)
;         : [a0] "v"(va[0]), [a1] "v"(va[1]), [a2] "v"(va[2]), [a3] "v"(va[3]), [b0] "v"(vb[0]), [b1] "v"(vb[1]), [b2] "v"(vb[2]), [b3] "v"(vb[3]),
;           [sa] "s"(sa), [sb] "s"(sb), [l] "s"(lds)
;         : "memory", "scc");
;     ...
;     auto issue = [&](int kt, int st) {
;         glds_tile8(va, vb, a0p + (size_t)kt * kstepA, Btile + (size_t)kt * 64, __builtin_amdgcn_readfirstlane(lds0 + st * 32768));
;     };
;     const int sw0 = (quad ^ (l16 >> 1)) * 16;
;     const int aoffb = (wr * 64 + l16) * 128, boffb = 16384 + (wc * 64 + l16) * 128;
;     if (!first_issued) issue(0, 0);
; #pragma unroll 1
;     for (int kt = 0; kt < nk; ++kt) {
;         asm volatile("s_waitcnt vmcnt(0)\n\ts_barrier" ::: "memory");
;         if (kt + 1 < nk) issue(kt + 1, (kt + 1) & 1);
.LBB0_239:
	s_add_i32 s27, s22, 0x8000
	s_and_b32 s28, s27, 0x8000
	s_add_i32 s28, s28, s17
	s_cmp_lg_u32 s22, 0x18000
	s_waitcnt vmcnt(0)
	s_barrier
	s_cbranch_scc0 .LBB0_238
	s_mov_b32 s31, m0
	s_mov_b32 m0, s28
	s_nop 0
	global_load_lds_dwordx4 v66, s[40:41]
	s_add_u32 m0, m0, 0x1000
	s_nop 0
	global_load_lds_dwordx4 v67, s[40:41]
	s_add_u32 m0, m0, 0x1000
	s_nop 0
	global_load_lds_dwordx4 v68, s[40:41]
	s_add_u32 m0, m0, 0x1000
	s_nop 0
	global_load_lds_dwordx4 v69, s[40:41]
	s_add_u32 m0, m0, 0x1000
	s_nop 0
	global_load_lds_dwordx4 v66, s[38:39]
	s_add_u32 m0, m0, 0x1000
	s_nop 0
	global_load_lds_dwordx4 v67, s[38:39]
	s_add_u32 m0, m0, 0x1000
	s_nop 0
	global_load_lds_dwordx4 v68, s[38:39]
	s_add_u32 m0, m0, 0x1000
	s_nop 0
	global_load_lds_dwordx4 v69, s[38:39]
	s_mov_b32 m0, s31
	s_branch .LBB0_238

; DEVI void glds_tile8(const unsigned (&va)[4], const unsigned (&vb)[4], const void* sa, const void* sb, unsigned lds) {
;     ...
;     asm volatile(
;         "s_mov_b32 %[keep], m0\n\t"
;         "s_mov_b32 m0, %[l]\n\ts_nop 0\n\tglobal_load_lds_dwordx4 %[a0], %[sa]\n\t"
;         "s_add_u32 m0, m0, 0x1000\n\ts_nop 0\n\tglobal_load_lds_dwordx4 %[a1], %[sa]\n\t"
;         "s_add_u32 m0, m0, 0x1000\n\ts_nop 0\n\tglobal_load_lds_dwordx4 %[a2], %[sa]\n\t"
;         "s_add_u32 m0, m0, 0x1000\n\ts_nop 0\n\tglobal_load_lds_dwordx4 %[a3], %[sa]\n\t"
;         "s_add_u32 m0, m0, 0x1000\n\ts_nop 0\n\tglobal_load_lds_dwordx4 %[b0], %[sb]\n\t"
;         "s_add_u32 m0, m0, 0x1000\n\ts_nop 0\n\tglobal_load_lds_dwordx4 %[b1], %[sb]\n\t"
;         "s_add_u32 m0, m0, 0x1000\n\ts_nop 0\n\tglobal_load_lds_dwordx4 %[b2], %[sb]\n\t"
;         "s_add_u32 m0, m0, 0x1000\n\ts_nop 0\n\tglobal_load_lds_dwordx4 %[b3], %[sb]\n\t"
;         "s_mov_b32 m0, %[keep]"
;         : [keep] "=&s"(keep)
;         : [a0] "v"(va[0]), [a1] "v"(va[1]), [a2] "v"(va[2]), [a3] "v"(va[3]), [b0] "v"(vb[0]), [b1] "v"(vb[1]), [b2] "v"(vb[2]), [b3] "v"(vb[3]),
;           [sa] "s"(sa), [sb] "s"(sb), [l] "s"(lds)
;         : "memory", "scc");
;     ...
;     auto issue = [&](int kt, int st) {
;         glds_tile8(va, vb, a0p + (size_t)kt * kstepA, Btile + (size_t)kt * 64, __builtin_amdgcn_readfirstlane(lds0 + st * 32768));
;     };
;     const int sw0 = (quad ^ (l16 >> 1)) * 16;
;     const int aoffb = (wr * 64 + l16) * 128, boffb = 16384 + (wc * 64 + l16) * 128;
;     if (!first_issued) issue(0, 0);
; #pragma unroll 1
;     for (int kt = 0; kt < nk; ++kt) {
;         asm volatile("s_waitcnt vmcnt(0)\n\ts_barrier" ::: "memory");
;         if (kt + 1 < nk) issue(kt + 1, (kt + 1) & 1);
.LBB0_758:
	s_add_i32 s66, s65, 0x8000
	s_and_b32 s40, s66, 0x8000
	s_add_i32 s40, s47, s40
	s_cmp_lt_u32 s64, 43
	s_waitcnt vmcnt(0)
	s_barrier
	s_cbranch_scc0 .LBB0_757
	s_mov_b32 s41, m0
	s_mov_b32 m0, s40
	s_nop 0
	global_load_lds_dwordx4 v0, s[38:39]
	s_add_u32 m0, m0, 0x1000
	s_nop 0
	global_load_lds_dwordx4 v70, s[38:39]
	s_add_u32 m0, m0, 0x1000
	s_nop 0
	global_load_lds_dwordx4 v71, s[38:39]
	s_add_u32 m0, m0, 0x1000
	s_nop 0
	global_load_lds_dwordx4 v72, s[38:39]
	s_add_u32 m0, m0, 0x1000
	s_nop 0
	global_load_lds_dwordx4 v0, s[34:35]
	s_add_u32 m0, m0, 0x1000
	s_nop 0
	global_load_lds_dwordx4 v70, s[34:35]
	s_add_u32 m0, m0, 0x1000
	s_nop 0
	global_load_lds_dwordx4 v71, s[34:35]
	s_add_u32 m0, m0, 0x1000
	s_nop 0
	global_load_lds_dwordx4 v72, s[34:35]
	s_mov_b32 m0, s41
	s_branch .LBB0_757

;     ...
;     auto issue = [&](int kt, int st) {
;         glds_tile8(va, vb, a0p + (size_t)kt * kstepA, Btile + (size_t)kt * 64, __builtin_amdgcn_readfirstlane(lds0 + st * 32768));
;     };
;     const int sw0 = (quad ^ (l16 >> 1)) * 16;
;     const int aoffb = (wr * 64 + l16) * 128, boffb = 16384 + (wc * 64 + l16) * 128;
;     if (!first_issued) issue(0, 0);
; #pragma unroll 1
;     for (int kt = 0; kt < nk; ++kt) {
;         asm volatile("s_waitcnt vmcnt(0)\n\ts_barrier" ::: "memory");
;         if (kt + 1 < nk) issue(kt + 1, (kt + 1) & 1);
.LBB0_789:
	s_add_i32 s34, s31, 0x8000
	s_and_b32 s24, s34, 0x8000
	s_add_i32 s24, s27, s24
	s_cmp_lg_u32 s31, 0
	s_cbranch_scc1 .Lffn_fullw
	s_cmp_eq_u32 s17, 0
	s_cbranch_scc1 .Lffn_fullw
	s_waitcnt vmcnt(8)
	s_branch .Lffn_bar2

; DEVI void glds_tile8(const unsigned (&va)[4], const unsigned (&vb)[4], const void* sa, const void* sb, unsigned lds) {
;     ...
;     asm volatile(
;         "s_mov_b32 %[keep], m0\n\t"
;         "s_mov_b32 m0, %[l]\n\ts_nop 0\n\tglobal_load_lds_dwordx4 %[a0], %[sa]\n\t"
;         "s_add_u32 m0, m0, 0x1000\n\ts_nop 0\n\tglobal_load_lds_dwordx4 %[a1], %[sa]\n\t"
;         "s_add_u32 m0, m0, 0x1000\n\ts_nop 0\n\tglobal_load_lds_dwordx4 %[a2], %[sa]\n\t"
;         "s_add_u32 m0, m0, 0x1000\n\ts_nop 0\n\tglobal_load_lds_dwordx4 %[a3], %[sa]\n\t"
;         "s_add_u32 m0, m0, 0x1000\n\ts_nop 0\n\tglobal_load_lds_dwordx4 %[b0], %[sb]\n\t"
;         "s_add_u32 m0, m0, 0x1000\n\ts_nop 0\n\tglobal_load_lds_dwordx4 %[b1], %[sb]\n\t"
;         "s_add_u32 m0, m0, 0x1000\n\ts_nop 0\n\tglobal_load_lds_dwordx4 %[b2], %[sb]\n\t"
;         "s_add_u32 m0, m0, 0x1000\n\ts_nop 0\n\tglobal_load_lds_dwordx4 %[b3], %[sb]\n\t"
;         "s_mov_b32 m0, %[keep]"
;         : [keep] "=&s"(keep)
;         : [a0] "v"(va[0]), [a1] "v"(va[1]), [a2] "v"(va[2]), [a3] "v"(va[3]), [b0] "v"(vb[0]), [b1] "v"(vb[1]), [b2] "v"(vb[2]), [b3] "v"(vb[3]),
;           [sa] "s"(sa), [sb] "s"(sb), [l] "s"(lds)
;         : "memory", "scc");
;     ...
;     auto issue = [&](int kt, int st) {
;         glds_tile8(va, vb, a0p + (size_t)kt * kstepA, Btile + (size_t)kt * 64, __builtin_amdgcn_readfirstlane(lds0 + st * 32768));
;     };
;     const int sw0 = (quad ^ (l16 >> 1)) * 16;
;     const int aoffb = (wr * 64 + l16) * 128, boffb = 16384 + (wc * 64 + l16) * 128;
;     if (!first_issued) issue(0, 0);
; #pragma unroll 1
;     for (int kt = 0; kt < nk; ++kt) {
;         asm volatile("s_waitcnt vmcnt(0)\n\ts_barrier" ::: "memory");
;         if (kt + 1 < nk) issue(kt + 1, (kt + 1) & 1);
.Lffn_bar2:
	s_cmp_lg_u32 s31, 0x78000
	s_barrier
	s_cbranch_scc0 .LBB0_788
	s_mov_b32 s25, m0
	s_mov_b32 m0, s24
	s_nop 0
	global_load_lds_dwordx4 v0, s[14:15]
	s_add_u32 m0, m0, 0x1000
	s_nop 0
	global_load_lds_dwordx4 v68, s[14:15]
	s_add_u32 m0, m0, 0x1000
	s_nop 0
	global_load_lds_dwordx4 v69, s[14:15]
	s_add_u32 m0, m0, 0x1000
	s_nop 0
	global_load_lds_dwordx4 v71, s[14:15]
	s_add_u32 m0, m0, 0x1000
	s_nop 0
	global_load_lds_dwordx4 v0, s[10:11]
	s_add_u32 m0, m0, 0x1000
	s_nop 0
	global_load_lds_dwordx4 v68, s[10:11]
	s_add_u32 m0, m0, 0x1000
	s_nop 0
	global_load_lds_dwordx4 v69, s[10:11]
	s_add_u32 m0, m0, 0x1000
	s_nop 0
	global_load_lds_dwordx4 v71, s[10:11]
	s_mov_b32 m0, s25
	s_branch .LBB0_788
